# IDX score loop: per-iteration wait counts only the K-tile loads (vmcnt(4)), no longer the previous iteration's four score stores; full drain moved in front of the loop
# baseline (speedup 1.0000x reference)
; #define LAS __attribute__((address_space(3)))
; __device__ __forceinline__ void idx_unit(bf16* QB, float* SC, int* SEL, const float* qg, const float* kg, int b, int tp, LAS unsigned char* wl, int lane, bool do_norm) {
;     ...
;         bf16x8 af[2][4];
; #pragma unroll
;         for (int q2 = 0; q2 < 2; ++q2) { const bf16* ap = QB + (row + 2 * q2 + (n >> 4)) * NBP + CQI + (n & 15) * 64 + 8 * hi;
; #pragma unroll
;           for (int ks = 0; ks < 4; ++ks) af[q2][ks] = *(const bf16x8*)(ap + 16 * ks); }
;         float w[4][8];
; #pragma unroll
;         for (int a = 0; a < 4; ++a)
; #pragma unroll
;             for (int r = 0; r < 8; ++r) { const int hh = (r & 3) + 8 * (r >> 2) + 4 * hi; w[a][r] = 0.25f * bflo((unsigned)QB[(row + a) * NBP + CWI + hh]); }
;         float* scw0 = SC + (row + hi) * SEQ + n; float* scw1 = scw0 + 2 * (size_t)SEQ;
;         const int r8 = lane >> 3, c8 = lane & 7;
;         const bf16* kg8 = QB + (rowbase + r8) * NBP + CKI + c8 * 8;
;         LAS unsigned char* sdst = wl + r8 * 144 + c8 * 16;
;         const LAS unsigned char* fsrc = wl + n * 144 + 16 * hi;
;         bf16x8 cur[8];
; #pragma unroll
;         for (int i = 0; i < 8; ++i) cur[i] = *(const bf16x8*)(kg8 + (size_t)(8 * i) * NBP);
.LBB0_241:
	s_and_b64 vcc, exec, s[4:5]
	v_writelane_b32 v250, s11, 33
	s_cbranch_vccz .LBB0_561
	v_readlane_b32 s8, v253, 53
	v_readlane_b32 s9, v253, 54
	v_or_b32_e32 v2, s2, v108
	s_movk_i32 s11, 0x2200
	v_mov_b64_e32 v[0:1], s[8:9]
	v_mad_u64_u32 v[2:3], s[4:5], v2, s11, v[0:1]
	v_mad_i32_i24 v3, s79, v212, v3
	v_lshl_add_u64 v[2:3], v[2:3], 0, v[182:183]
	v_lshl_add_u64 v[2:3], v[2:3], 0, v[128:129]
	s_mov_b64 s[12:13], 0x1800
	v_lshl_add_u64 v[4:5], v[2:3], 0, s[12:13]
	v_add_co_u32_e32 v2, vcc, 0x1000, v2
	v_lshl_add_u64 v[18:19], s[0:1], 0, v[114:115]
	s_nop 0
	v_addc_co_u32_e32 v3, vcc, 0, v3, vcc
	global_load_dwordx4 v[32:35], v[4:5], off offset:32
	global_load_dwordx4 v[36:39], v[4:5], off offset:64
	global_load_dwordx4 v[40:43], v[2:3], off offset:2048
	global_load_dwordx4 v[44:47], v[4:5], off offset:96
	v_or_b32_e32 v2, s2, v110
	v_mad_u64_u32 v[2:3], s[4:5], v2, s11, v[0:1]
	v_mad_i32_i24 v3, s79, v212, v3
	v_lshl_add_u64 v[2:3], v[2:3], 0, v[182:183]
	v_lshl_add_u64 v[2:3], v[2:3], 0, v[128:129]
	s_movk_i32 s4, 0x1000
	v_lshl_add_u64 v[4:5], v[2:3], 0, s[12:13]
	v_add_co_u32_e32 v2, vcc, s4, v2
	s_mul_i32 s4, s79, 0x2200
	s_mul_hi_u32 s5, s2, 0x2200
	s_add_i32 s5, s5, s4
	s_mul_i32 s4, s2, 0x2200
	s_add_u32 s4, s8, s4
	v_addc_co_u32_e32 v3, vcc, 0, v3, vcc
	s_addc_u32 s5, s9, s5
	global_load_dwordx4 v[48:51], v[4:5], off offset:32
	global_load_dwordx4 v[52:55], v[4:5], off offset:64
	global_load_dwordx4 v[56:59], v[2:3], off offset:2048
	global_load_dwordx4 v[60:63], v[4:5], off offset:96
	v_lshl_add_u64 v[2:3], v[112:113], 1, s[4:5]
	s_mov_b64 s[4:5], 0x2080
	v_lshl_add_u64 v[4:5], v[2:3], 0, s[4:5]
	v_add_co_u32_e32 v6, vcc, s10, v2
	s_mov_b64 s[4:5], 0x4280
	s_nop 0
	v_addc_co_u32_e32 v7, vcc, 0, v3, vcc
	v_lshl_add_u64 v[8:9], v[2:3], 0, s[4:5]
	s_movk_i32 s4, 0x4000
	v_add_co_u32_e32 v10, vcc, s4, v2
	s_mov_b64 s[4:5], 0x6480
	s_nop 0
	v_addc_co_u32_e32 v11, vcc, 0, v3, vcc
	global_load_dwordx2 v[6:7], v[6:7], off offset:128
	s_nop 0
	global_load_dwordx2 v[10:11], v[10:11], off offset:640
	s_nop 0
	global_load_dwordx2 v[8:9], v[8:9], off offset:16
	s_nop 0
	global_load_dwordx2 v[4:5], v[4:5], off offset:16
	v_lshl_add_u64 v[12:13], v[2:3], 0, s[4:5]
	s_movk_i32 s4, 0x6000
	v_add_co_u32_e32 v14, vcc, s4, v2
	s_mov_b64 s[4:5], 0x8680
	s_nop 0
	v_addc_co_u32_e32 v15, vcc, 0, v3, vcc
	v_lshl_add_u64 v[16:17], v[2:3], 0, s[4:5]
	s_mov_b32 s5, 0x8000
	v_mad_u64_u32 v[0:1], s[0:1], v18, s11, v[0:1]
	v_add_co_u32_e32 v2, vcc, s5, v2
	v_mad_i32_i24 v1, v19, s11, v1
	v_mov_b32_e32 v131, v183
	v_addc_co_u32_e32 v3, vcc, 0, v3, vcc
	v_lshl_add_u64 v[0:1], v[0:1], 0, v[130:131]
	s_mov_b32 s0, 0x79000
	global_load_dwordx2 v[14:15], v[14:15], off offset:1152
	s_nop 0
	global_load_dwordx2 v[2:3], v[2:3], off offset:1664
	s_nop 0
	global_load_dwordx2 v[16:17], v[16:17], off offset:16
	s_nop 0
	global_load_dwordx2 v[12:13], v[12:13], off offset:16
	v_add_co_u32_e32 v18, vcc, s0, v0
	s_mov_b32 s0, 0x68000
	s_nop 0
	v_addc_co_u32_e32 v19, vcc, 0, v1, vcc
	v_add_co_u32_e32 v20, vcc, s0, v0
	s_mov_b32 s0, 0x57000
	s_nop 0
	v_addc_co_u32_e32 v21, vcc, 0, v1, vcc
	global_load_dwordx4 v[92:95], v[18:19], off
	global_load_dwordx4 v[84:87], v[20:21], off
	v_add_co_u32_e32 v18, vcc, s0, v0
	s_mov_b32 s0, 0x46000
	s_nop 0
	v_addc_co_u32_e32 v19, vcc, 0, v1, vcc
	v_add_co_u32_e32 v20, vcc, s0, v0
	s_mov_b32 s0, 0
	s_nop 0
	v_addc_co_u32_e32 v21, vcc, 0, v1, vcc
	global_load_dwordx4 v[88:91], v[18:19], off
	global_load_dwordx4 v[76:79], v[20:21], off
	v_add_co_u32_e32 v18, vcc, 0x35000, v0
	v_lshl_add_u64 v[132:133], v[0:1], 0, s[14:15]
	s_nop 0
	v_addc_co_u32_e32 v19, vcc, 0, v1, vcc
	v_add_co_u32_e32 v20, vcc, 0x24000, v0
	s_nop 1
	v_addc_co_u32_e32 v21, vcc, 0, v1, vcc
	global_load_dwordx4 v[80:83], v[18:19], off
	global_load_dwordx4 v[68:71], v[20:21], off
	v_add_co_u32_e32 v18, vcc, 0x13000, v0
	s_nop 1
	v_addc_co_u32_e32 v19, vcc, 0, v1, vcc
	v_add_co_u32_e32 v20, vcc, 0x2000, v0
	s_nop 1
	v_addc_co_u32_e32 v21, vcc, 0, v1, vcc
	global_load_dwordx4 v[72:75], v[18:19], off
	global_load_dwordx4 v[64:67], v[20:21], off
	s_waitcnt vmcnt(15)
	v_lshlrev_b32_e32 v18, 16, v6
	v_and_b32_e32 v6, 0xffff0000, v6
	v_mul_f32_e32 v217, 0x3e800000, v6
	v_lshlrev_b32_e32 v6, 16, v7
	v_mul_f32_e32 v218, 0x3e800000, v6
	v_and_b32_e32 v6, 0xffff0000, v7
	v_mul_f32_e32 v219, 0x3e800000, v6
	s_waitcnt vmcnt(12)
	v_lshlrev_b32_e32 v6, 16, v4
	v_and_b32_e32 v4, 0xffff0000, v4
	v_mul_f32_e32 v221, 0x3e800000, v4
	v_lshlrev_b32_e32 v4, 16, v5
	v_mul_f32_e32 v222, 0x3e800000, v4
	v_and_b32_e32 v4, 0xffff0000, v5
	v_mul_f32_e32 v223, 0x3e800000, v4
	v_lshlrev_b32_e32 v4, 16, v10
	v_mul_f32_e32 v224, 0x3e800000, v4
	v_and_b32_e32 v4, 0xffff0000, v10
	v_mul_f32_e32 v225, 0x3e800000, v4
	v_lshlrev_b32_e32 v4, 16, v11
	v_mul_f32_e32 v226, 0x3e800000, v4
	v_and_b32_e32 v4, 0xffff0000, v11
	v_mul_f32_e32 v227, 0x3e800000, v4
	v_lshlrev_b32_e32 v4, 16, v8
	v_mul_f32_e32 v228, 0x3e800000, v4
	v_and_b32_e32 v4, 0xffff0000, v8
	v_mul_f32_e32 v229, 0x3e800000, v4
	v_lshlrev_b32_e32 v4, 16, v9
	v_mul_f32_e32 v230, 0x3e800000, v4
	v_and_b32_e32 v4, 0xffff0000, v9
	v_mul_f32_e32 v231, 0x3e800000, v4
	s_waitcnt vmcnt(11)
	v_lshlrev_b32_e32 v4, 16, v14
	v_mul_f32_e32 v232, 0x3e800000, v4
	v_and_b32_e32 v4, 0xffff0000, v14
	v_mul_f32_e32 v233, 0x3e800000, v4
	v_lshlrev_b32_e32 v4, 16, v15
	v_mul_f32_e32 v234, 0x3e800000, v4
	v_and_b32_e32 v4, 0xffff0000, v15
	v_mul_f32_e32 v235, 0x3e800000, v4
	s_waitcnt vmcnt(8)
	v_lshlrev_b32_e32 v4, 16, v12
	v_mul_f32_e32 v236, 0x3e800000, v4
	v_and_b32_e32 v4, 0xffff0000, v12
	v_mul_f32_e32 v237, 0x3e800000, v4
	v_lshlrev_b32_e32 v4, 16, v13
	v_mul_f32_e32 v238, 0x3e800000, v4
	v_and_b32_e32 v4, 0xffff0000, v13
	v_mul_f32_e32 v239, 0x3e800000, v4
	v_lshlrev_b32_e32 v4, 16, v2
	v_and_b32_e32 v2, 0xffff0000, v2
	v_mul_f32_e32 v241, 0x3e800000, v2
	v_lshlrev_b32_e32 v2, 16, v3
	v_mul_f32_e32 v242, 0x3e800000, v2
	v_and_b32_e32 v2, 0xffff0000, v3
	v_mul_f32_e32 v243, 0x3e800000, v2
	v_lshlrev_b32_e32 v2, 16, v16
	v_mul_f32_e32 v244, 0x3e800000, v2
	v_and_b32_e32 v2, 0xffff0000, v16
	v_mul_f32_e32 v245, 0x3e800000, v2
	v_lshlrev_b32_e32 v2, 16, v17
	v_mul_f32_e32 v246, 0x3e800000, v2
	v_and_b32_e32 v2, 0xffff0000, v17
	v_mul_f32_e32 v247, 0x3e800000, v2
	v_lshl_add_u64 v[2:3], s[2:3], 0, v[106:107]
	v_lshlrev_b64 v[2:3], 14, v[2:3]
	v_mul_f32_e32 v131, 0x3e800000, v18
	v_mul_f32_e32 v220, 0x3e800000, v6
	v_mul_f32_e32 v240, 0x3e800000, v4
	v_lshl_add_u64 v[134:135], v[126:127], 0, v[2:3]
	s_waitcnt vmcnt(0)
; #define LAS __attribute__((address_space(3)))
; #define LDS_WAIT() asm volatile("s_waitcnt lgkmcnt(0)" ::: "memory")
; __device__ __forceinline__ void idx_unit(bf16* QB, float* SC, int* SEL, const float* qg, const float* kg, int b, int tp, LAS unsigned char* wl, int lane, bool do_norm) {
;     ...
;         for (int s0 = 0; s0 < ce; s0 += 64) {
; #pragma unroll
;             for (int i = 0; i < 8; ++i) *(LAS bf16x8*)(sdst + (8 * i) * 144) = cur[i];
;             const int sn = (s0 + 64 < ce) ? s0 + 64 : 0;
; #pragma unroll
;             for (int i = 0; i < 8; ++i) cur[i] = *(const bf16x8*)(kg8 + (size_t)(sn + 8 * i) * NBP);
;             LDS_WAIT();
; #pragma unroll
;             for (int tt = 0; tt < 2; ++tt) {
;                 f32x16 acc0, acc1;
; #pragma unroll
;                 for (int r = 0; r < 16; ++r) { acc0[r] = 0.f; acc1[r] = 0.f; }
; #pragma unroll
;                 for (int ks = 0; ks < 4; ++ks) { const bf16x8 bfr = *(const LAS bf16x8*)(fsrc + tt * 32 * 144 + 32 * ks);
;                     acc0 = __builtin_amdgcn_mfma_f32_32x32x16_bf16(af[0][ks], bfr, acc0, 0, 0, 0); acc1 = __builtin_amdgcn_mfma_f32_32x32x16_bf16(af[1][ks], bfr, acc1, 0, 0, 0); }
;                 float pa = 0.f, pb = 0.f, pc = 0.f, pd = 0.f;
; #pragma unroll
;                 for (int r = 0; r < 8; ++r) { pa += w[0][r] * (__builtin_fmaxf(acc0[r], 0.f) * 0.125f); pb += w[1][r] * (__builtin_fmaxf(acc0[8 + r], 0.f) * 0.125f);
;                                               pc += w[2][r] * (__builtin_fmaxf(acc1[r], 0.f) * 0.125f); pd += w[3][r] * (__builtin_fmaxf(acc1[8 + r], 0.f) * 0.125f); }
;                 const float snd0 = hi ? pa : pb, snd1 = hi ? pc : pd; const float rcv0 = __shfl_xor(snd0, 32), rcv1 = __shfl_xor(snd1, 32);
;                 scw0[s0 + 32 * tt] = (hi ? pb : pa) + rcv0;
;                 scw1[s0 + 32 * tt] = (hi ? pd : pc) + rcv1;
.LBB0_243:
	s_add_i32 s3, s0, 64
	s_cmp_lt_i32 s0, s7
	s_cselect_b64 s[0:1], -1, 0
	s_and_b64 vcc, s[0:1], exec
	s_cselect_b32 s4, s3, 0
	v_mad_u64_u32 v[0:1], s[0:1], s4, v212, v[132:133]
	s_waitcnt vmcnt(4)
	ds_write_b128 v101, v[64:67]
	ds_write_b128 v101, v[72:75] offset:1152
	ds_write_b128 v101, v[68:71] offset:2304
	ds_write_b128 v101, v[80:83] offset:3456
	ds_write_b128 v101, v[76:79] offset:4608
	ds_write_b128 v101, v[88:91] offset:5760
	ds_write_b128 v101, v[84:87] offset:6912
	ds_write_b128 v101, v[92:95] offset:8064
	s_or_b32 s0, s4, 8
	global_load_dwordx4 v[64:67], v[0:1], off
	v_mad_u64_u32 v[0:1], s[0:1], s0, v212, v[132:133]
	s_or_b32 s0, s4, 16
	global_load_dwordx4 v[72:75], v[0:1], off
	v_mad_u64_u32 v[0:1], s[0:1], s0, v212, v[132:133]
	s_or_b32 s0, s4, 24
	global_load_dwordx4 v[68:71], v[0:1], off
	v_mad_u64_u32 v[0:1], s[0:1], s0, v212, v[132:133]
	s_or_b32 s0, s4, 32
	global_load_dwordx4 v[80:83], v[0:1], off
	v_mad_u64_u32 v[0:1], s[0:1], s0, v212, v[132:133]
	s_or_b32 s0, s4, 40
	global_load_dwordx4 v[76:79], v[0:1], off
	v_mad_u64_u32 v[0:1], s[0:1], s0, v212, v[132:133]
	s_or_b32 s0, s4, 48
	global_load_dwordx4 v[88:91], v[0:1], off
	v_mad_u64_u32 v[0:1], s[0:1], s0, v212, v[132:133]
	s_or_b32 s0, s4, 56
	global_load_dwordx4 v[84:87], v[0:1], off
	v_mad_u64_u32 v[0:1], s[0:1], s0, v212, v[132:133]
	global_load_dwordx4 v[92:95], v[0:1], off
	s_waitcnt lgkmcnt(0)
	ds_read_b128 v[0:3], v103
	ds_read_b128 v[120:123], v103 offset:32
	s_waitcnt lgkmcnt(1)
	v_mfma_f32_32x32x16_bf16 v[16:31], v[40:43], v[0:3], 0
	v_add_co_u32_e64 v136, s[0:1], s5, v134
	s_nop 1
	v_addc_co_u32_e64 v137, s[0:1], 0, v135, s[0:1]
	s_mov_b64 s[0:1], 0x100
	v_mfma_f32_32x32x16_bf16 v[0:15], v[56:59], v[0:3], 0
	s_waitcnt lgkmcnt(0)
	v_mfma_f32_32x32x16_bf16 v[0:15], v[48:51], v[120:123], v[0:15]
	v_mfma_f32_32x32x16_bf16 v[16:31], v[32:35], v[120:123], v[16:31]
	ds_read_b128 v[120:123], v103 offset:64
	s_waitcnt lgkmcnt(0)
	v_mfma_f32_32x32x16_bf16 v[0:15], v[52:55], v[120:123], v[0:15]
	v_mfma_f32_32x32x16_bf16 v[16:31], v[36:39], v[120:123], v[16:31]
	ds_read_b128 v[120:123], v103 offset:96
	s_waitcnt lgkmcnt(0)
	v_mfma_f32_32x32x16_bf16 v[0:15], v[60:63], v[120:123], v[0:15]
	v_mfma_f32_32x32x16_bf16 v[16:31], v[44:47], v[120:123], v[16:31]
	s_nop 10
	v_max_f32_e32 v0, v0, v0
	v_max_f32_e32 v0, 0, v0
	v_max_f32_e32 v1, v1, v1
	v_mul_f32_e32 v0, 0x3e000000, v0
	v_max_f32_e32 v1, 0, v1
	v_fma_f32 v0, v232, v0, 0
	v_max_f32_e32 v8, v8, v8
	v_mul_f32_e32 v1, 0x3e000000, v1
	v_max_f32_e32 v8, 0, v8
	v_fmac_f32_e32 v0, v233, v1
	v_max_f32_e32 v1, v9, v9
	v_max_f32_e32 v16, v16, v16
	v_mul_f32_e32 v8, 0x3e000000, v8
	v_max_f32_e32 v1, 0, v1
	v_max_f32_e32 v16, 0, v16
	v_fma_f32 v8, v240, v8, 0
	v_max_f32_e32 v17, v17, v17
	v_mul_f32_e32 v1, 0x3e000000, v1
	v_mul_f32_e32 v16, 0x3e000000, v16
	v_max_f32_e32 v17, 0, v17
	v_fmac_f32_e32 v8, v241, v1
	v_max_f32_e32 v1, v18, v18
	v_fma_f32 v16, v131, v16, 0
	v_max_f32_e32 v24, v24, v24
	v_mul_f32_e32 v17, 0x3e000000, v17
	v_max_f32_e32 v1, 0, v1
	v_max_f32_e32 v24, 0, v24
	v_fmac_f32_e32 v16, v217, v17
	v_max_f32_e32 v17, v25, v25
	v_mul_f32_e32 v1, 0x3e000000, v1
	v_mul_f32_e32 v24, 0x3e000000, v24
	v_max_f32_e32 v17, 0, v17
	v_fmac_f32_e32 v16, v218, v1
	v_max_f32_e32 v1, v26, v26
	v_fma_f32 v24, v224, v24, 0
	v_mul_f32_e32 v17, 0x3e000000, v17
	v_max_f32_e32 v1, 0, v1
	v_fmac_f32_e32 v24, v225, v17
	v_mul_f32_e32 v1, 0x3e000000, v1
	v_fmac_f32_e32 v24, v226, v1
	v_max_f32_e32 v1, v2, v2
	v_max_f32_e32 v1, 0, v1
	v_mul_f32_e32 v1, 0x3e000000, v1
	v_fmac_f32_e32 v0, v234, v1
	v_max_f32_e32 v1, v10, v10
	v_max_f32_e32 v1, 0, v1
	v_mul_f32_e32 v1, 0x3e000000, v1
	v_fmac_f32_e32 v8, v242, v1
	v_max_f32_e32 v1, v19, v19
	v_max_f32_e32 v1, 0, v1
	v_mul_f32_e32 v1, 0x3e000000, v1
	v_fmac_f32_e32 v16, v219, v1
	v_max_f32_e32 v1, v27, v27
	v_max_f32_e32 v1, 0, v1
	v_mul_f32_e32 v1, 0x3e000000, v1
	v_fmac_f32_e32 v24, v227, v1
	v_max_f32_e32 v1, v3, v3
	v_max_f32_e32 v1, 0, v1
	v_mul_f32_e32 v1, 0x3e000000, v1
	v_fmac_f32_e32 v0, v235, v1
	v_max_f32_e32 v1, v11, v11
	v_max_f32_e32 v1, 0, v1
	v_mul_f32_e32 v1, 0x3e000000, v1
	v_fmac_f32_e32 v8, v243, v1
	v_max_f32_e32 v1, v20, v20
	v_max_f32_e32 v1, 0, v1
	v_mul_f32_e32 v1, 0x3e000000, v1
	v_fmac_f32_e32 v16, v220, v1
	v_max_f32_e32 v1, v28, v28
	v_max_f32_e32 v1, 0, v1
	v_mul_f32_e32 v1, 0x3e000000, v1
	v_fmac_f32_e32 v24, v228, v1
	v_max_f32_e32 v1, v4, v4
	v_max_f32_e32 v1, 0, v1
	v_mul_f32_e32 v1, 0x3e000000, v1
	v_fmac_f32_e32 v0, v236, v1
	v_max_f32_e32 v1, v12, v12
	v_max_f32_e32 v1, 0, v1
	v_mul_f32_e32 v1, 0x3e000000, v1
	v_fmac_f32_e32 v8, v244, v1
	v_max_f32_e32 v1, v21, v21
	v_max_f32_e32 v1, 0, v1
	v_mul_f32_e32 v1, 0x3e000000, v1
	v_fmac_f32_e32 v16, v221, v1
	v_max_f32_e32 v1, v29, v29
	v_max_f32_e32 v1, 0, v1
	v_mul_f32_e32 v1, 0x3e000000, v1
	v_fmac_f32_e32 v24, v229, v1
	v_max_f32_e32 v1, v5, v5
	v_max_f32_e32 v1, 0, v1
	v_mul_f32_e32 v1, 0x3e000000, v1
	v_fmac_f32_e32 v0, v237, v1
	v_max_f32_e32 v1, v13, v13
	v_max_f32_e32 v1, 0, v1
	v_mul_f32_e32 v1, 0x3e000000, v1
	v_fmac_f32_e32 v8, v245, v1
	v_max_f32_e32 v1, v22, v22
	v_max_f32_e32 v1, 0, v1
	v_mul_f32_e32 v1, 0x3e000000, v1
	v_fmac_f32_e32 v16, v222, v1
	v_max_f32_e32 v1, v30, v30
	v_max_f32_e32 v1, 0, v1
	v_mul_f32_e32 v1, 0x3e000000, v1
	v_fmac_f32_e32 v24, v230, v1
	v_max_f32_e32 v1, v6, v6
	v_max_f32_e32 v1, 0, v1
	v_mul_f32_e32 v1, 0x3e000000, v1
	v_fmac_f32_e32 v0, v238, v1
	v_max_f32_e32 v1, v14, v14
	v_max_f32_e32 v1, 0, v1
	v_mul_f32_e32 v1, 0x3e000000, v1
	v_fmac_f32_e32 v8, v246, v1
	v_max_f32_e32 v1, v23, v23
	v_max_f32_e32 v1, 0, v1
	v_mul_f32_e32 v1, 0x3e000000, v1
	v_fmac_f32_e32 v16, v223, v1
	v_max_f32_e32 v1, v31, v31
	v_max_f32_e32 v1, 0, v1
	v_mul_f32_e32 v1, 0x3e000000, v1
	v_fmac_f32_e32 v24, v231, v1
	v_max_f32_e32 v1, v7, v7
	v_max_f32_e32 v1, 0, v1
	v_mul_f32_e32 v1, 0x3e000000, v1
	v_fmac_f32_e32 v0, v239, v1
	v_max_f32_e32 v1, v15, v15
	v_max_f32_e32 v1, 0, v1
	v_mul_f32_e32 v1, 0x3e000000, v1
	v_fmac_f32_e32 v8, v247, v1
	v_cndmask_b32_e64 v1, v16, v24, s[40:41]
	v_cndmask_b32_e64 v2, v0, v8, s[40:41]
	ds_bpermute_b32 v1, v97, v1
	ds_bpermute_b32 v2, v97, v2
	v_cndmask_b32_e64 v3, v24, v16, s[40:41]
	v_cndmask_b32_e64 v0, v8, v0, s[40:41]
	ds_read_b128 v[120:123], v103 offset:4640
	s_waitcnt lgkmcnt(2)
; #define LAS __attribute__((address_space(3)))
; #define LDS_WAIT() asm volatile("s_waitcnt lgkmcnt(0)" ::: "memory")
; __device__ __forceinline__ void idx_unit(bf16* QB, float* SC, int* SEL, const float* qg, const float* kg, int b, int tp, LAS unsigned char* wl, int lane, bool do_norm) {
;     ...
;             for (int tt = 0; tt < 2; ++tt) {
;                 f32x16 acc0, acc1;
; #pragma unroll
;                 for (int r = 0; r < 16; ++r) { acc0[r] = 0.f; acc1[r] = 0.f; }
; #pragma unroll
;                 for (int ks = 0; ks < 4; ++ks) { const bf16x8 bfr = *(const LAS bf16x8*)(fsrc + tt * 32 * 144 + 32 * ks);
;                     acc0 = __builtin_amdgcn_mfma_f32_32x32x16_bf16(af[0][ks], bfr, acc0, 0, 0, 0); acc1 = __builtin_amdgcn_mfma_f32_32x32x16_bf16(af[1][ks], bfr, acc1, 0, 0, 0); }
;                 float pa = 0.f, pb = 0.f, pc = 0.f, pd = 0.f;
; #pragma unroll
;                 for (int r = 0; r < 8; ++r) { pa += w[0][r] * (__builtin_fmaxf(acc0[r], 0.f) * 0.125f); pb += w[1][r] * (__builtin_fmaxf(acc0[8 + r], 0.f) * 0.125f);
;                                               pc += w[2][r] * (__builtin_fmaxf(acc1[r], 0.f) * 0.125f); pd += w[3][r] * (__builtin_fmaxf(acc1[8 + r], 0.f) * 0.125f); }
;                 const float snd0 = hi ? pa : pb, snd1 = hi ? pc : pd; const float rcv0 = __shfl_xor(snd0, 32), rcv1 = __shfl_xor(snd1, 32);
;                 scw0[s0 + 32 * tt] = (hi ? pb : pa) + rcv0;
;                 scw1[s0 + 32 * tt] = (hi ? pd : pc) + rcv1;
;             }
;             LDS_WAIT();
;         }
	v_add_f32_e32 v1, v3, v1
	s_waitcnt lgkmcnt(1)
	v_add_f32_e32 v0, v0, v2
	global_store_dword v[134:135], v1, off
	global_store_dword v[136:137], v0, off
	ds_read_b128 v[0:3], v103 offset:4608
	s_waitcnt lgkmcnt(0)
	v_mfma_f32_32x32x16_bf16 v[16:31], v[40:43], v[0:3], 0
	v_mfma_f32_32x32x16_bf16 v[0:15], v[56:59], v[0:3], 0
	v_mfma_f32_32x32x16_bf16 v[0:15], v[48:51], v[120:123], v[0:15]
	v_mfma_f32_32x32x16_bf16 v[16:31], v[32:35], v[120:123], v[16:31]
	ds_read_b128 v[120:123], v103 offset:4672
	s_waitcnt lgkmcnt(0)
	v_mfma_f32_32x32x16_bf16 v[0:15], v[52:55], v[120:123], v[0:15]
	v_mfma_f32_32x32x16_bf16 v[16:31], v[36:39], v[120:123], v[16:31]
	ds_read_b128 v[120:123], v103 offset:4704
	s_waitcnt lgkmcnt(0)
	v_mfma_f32_32x32x16_bf16 v[0:15], v[60:63], v[120:123], v[0:15]
	v_mfma_f32_32x32x16_bf16 v[16:31], v[44:47], v[120:123], v[16:31]
	s_nop 10
	v_max_f32_e32 v0, v0, v0
	v_max_f32_e32 v0, 0, v0
	v_max_f32_e32 v1, v1, v1
	v_mul_f32_e32 v0, 0x3e000000, v0
	v_max_f32_e32 v1, 0, v1
	v_fma_f32 v0, v232, v0, 0
	v_max_f32_e32 v8, v8, v8
	v_mul_f32_e32 v1, 0x3e000000, v1
	v_max_f32_e32 v8, 0, v8
	v_fmac_f32_e32 v0, v233, v1
	v_max_f32_e32 v1, v9, v9
	v_max_f32_e32 v16, v16, v16
	v_mul_f32_e32 v8, 0x3e000000, v8
	v_max_f32_e32 v1, 0, v1
	v_max_f32_e32 v16, 0, v16
	v_fma_f32 v8, v240, v8, 0
	v_max_f32_e32 v17, v17, v17
	v_mul_f32_e32 v1, 0x3e000000, v1
	v_mul_f32_e32 v16, 0x3e000000, v16
	v_max_f32_e32 v17, 0, v17
	v_fmac_f32_e32 v8, v241, v1
	v_max_f32_e32 v1, v18, v18
	v_fma_f32 v16, v131, v16, 0
	v_max_f32_e32 v24, v24, v24
	v_mul_f32_e32 v17, 0x3e000000, v17
	v_max_f32_e32 v1, 0, v1
	v_max_f32_e32 v24, 0, v24
	v_fmac_f32_e32 v16, v217, v17
	v_max_f32_e32 v17, v25, v25
	v_mul_f32_e32 v1, 0x3e000000, v1
	v_mul_f32_e32 v24, 0x3e000000, v24
	v_max_f32_e32 v17, 0, v17
	v_fmac_f32_e32 v16, v218, v1
	v_max_f32_e32 v1, v26, v26
	v_fma_f32 v24, v224, v24, 0
	v_mul_f32_e32 v17, 0x3e000000, v17
	v_max_f32_e32 v1, 0, v1
	v_fmac_f32_e32 v24, v225, v17
	v_mul_f32_e32 v1, 0x3e000000, v1
	v_fmac_f32_e32 v24, v226, v1
	v_max_f32_e32 v1, v2, v2
	v_max_f32_e32 v1, 0, v1
	v_mul_f32_e32 v1, 0x3e000000, v1
	v_fmac_f32_e32 v0, v234, v1
	v_max_f32_e32 v1, v10, v10
	v_max_f32_e32 v1, 0, v1
	v_mul_f32_e32 v1, 0x3e000000, v1
	v_fmac_f32_e32 v8, v242, v1
	v_max_f32_e32 v1, v19, v19
	v_max_f32_e32 v1, 0, v1
	v_mul_f32_e32 v1, 0x3e000000, v1
	v_fmac_f32_e32 v16, v219, v1
	v_max_f32_e32 v1, v27, v27
	v_max_f32_e32 v1, 0, v1
	v_mul_f32_e32 v1, 0x3e000000, v1
	v_fmac_f32_e32 v24, v227, v1
	v_max_f32_e32 v1, v3, v3
	v_max_f32_e32 v1, 0, v1
	v_mul_f32_e32 v1, 0x3e000000, v1
	v_fmac_f32_e32 v0, v235, v1
	v_max_f32_e32 v1, v11, v11
	v_max_f32_e32 v1, 0, v1
	v_mul_f32_e32 v1, 0x3e000000, v1
	v_fmac_f32_e32 v8, v243, v1
	v_max_f32_e32 v1, v20, v20
	v_max_f32_e32 v1, 0, v1
	v_mul_f32_e32 v1, 0x3e000000, v1
	v_fmac_f32_e32 v16, v220, v1
	v_max_f32_e32 v1, v28, v28
	v_max_f32_e32 v1, 0, v1
	v_mul_f32_e32 v1, 0x3e000000, v1
	v_fmac_f32_e32 v24, v228, v1
	v_max_f32_e32 v1, v4, v4
	v_max_f32_e32 v1, 0, v1
	v_mul_f32_e32 v1, 0x3e000000, v1
	v_fmac_f32_e32 v0, v236, v1
	v_max_f32_e32 v1, v12, v12
	v_max_f32_e32 v1, 0, v1
	v_mul_f32_e32 v1, 0x3e000000, v1
	v_fmac_f32_e32 v8, v244, v1
	v_max_f32_e32 v1, v21, v21
	v_max_f32_e32 v1, 0, v1
	v_mul_f32_e32 v1, 0x3e000000, v1
	v_fmac_f32_e32 v16, v221, v1
	v_max_f32_e32 v1, v29, v29
	v_max_f32_e32 v1, 0, v1
	v_mul_f32_e32 v1, 0x3e000000, v1
	v_fmac_f32_e32 v24, v229, v1
	v_max_f32_e32 v1, v5, v5
	v_max_f32_e32 v1, 0, v1
	v_mul_f32_e32 v1, 0x3e000000, v1
	v_fmac_f32_e32 v0, v237, v1
	v_max_f32_e32 v1, v13, v13
	v_max_f32_e32 v1, 0, v1
	v_mul_f32_e32 v1, 0x3e000000, v1
	v_fmac_f32_e32 v8, v245, v1
	v_max_f32_e32 v1, v22, v22
	v_max_f32_e32 v1, 0, v1
	v_mul_f32_e32 v1, 0x3e000000, v1
	v_fmac_f32_e32 v16, v222, v1
	v_max_f32_e32 v1, v30, v30
	v_max_f32_e32 v1, 0, v1
	v_mul_f32_e32 v1, 0x3e000000, v1
	v_fmac_f32_e32 v24, v230, v1
	v_max_f32_e32 v1, v6, v6
	v_max_f32_e32 v1, 0, v1
	v_mul_f32_e32 v1, 0x3e000000, v1
	v_fmac_f32_e32 v0, v238, v1
	v_max_f32_e32 v1, v14, v14
	v_max_f32_e32 v1, 0, v1
	v_mul_f32_e32 v1, 0x3e000000, v1
	v_fmac_f32_e32 v8, v246, v1
	v_max_f32_e32 v1, v23, v23
	v_max_f32_e32 v1, 0, v1
	v_mul_f32_e32 v1, 0x3e000000, v1
	v_fmac_f32_e32 v16, v223, v1
	v_max_f32_e32 v1, v31, v31
	v_max_f32_e32 v1, 0, v1
	v_mul_f32_e32 v1, 0x3e000000, v1
	v_fmac_f32_e32 v24, v231, v1
	v_max_f32_e32 v1, v7, v7
	v_max_f32_e32 v1, 0, v1
	v_mul_f32_e32 v1, 0x3e000000, v1
	v_fmac_f32_e32 v0, v239, v1
	v_max_f32_e32 v1, v15, v15
	v_max_f32_e32 v1, 0, v1
	v_mul_f32_e32 v1, 0x3e000000, v1
	v_fmac_f32_e32 v8, v247, v1
	v_cndmask_b32_e64 v1, v16, v24, s[40:41]
	v_cndmask_b32_e64 v2, v0, v8, s[40:41]
	ds_bpermute_b32 v1, v97, v1
	ds_bpermute_b32 v2, v97, v2
	v_cndmask_b32_e64 v3, v24, v16, s[40:41]
	v_cndmask_b32_e64 v0, v8, v0, s[40:41]
	s_waitcnt lgkmcnt(1)
	v_add_f32_e32 v1, v3, v1
	s_waitcnt lgkmcnt(0)
	v_add_f32_e32 v0, v0, v2
	global_store_dword v[134:135], v1, off offset:128
	global_store_dword v[136:137], v0, off offset:128
	s_waitcnt lgkmcnt(0)
	v_lshl_add_u64 v[134:135], v[134:135], 0, s[0:1]
	s_mov_b32 s0, s3
	s_cbranch_vccnz .LBB0_243
; __device__ __forceinline__ unsigned fkey(float f) { const unsigned u = __builtin_bit_cast(unsigned, f); return (u & 0x80000000u) ? ~u : (u | 0x80000000u); }
; __device__ __forceinline__ void select_query(const float* sc, int* sel, int ce, int lane) {
;     const int nreg = ce >> 6;
;     unsigned key[64];
;     {
;         float raw[64];
; #pragma unroll
;         for (int g = 0; g < 8; ++g) {
;             if (8 * g < nreg) {
; #pragma unroll
;                 for (int j = 8 * g; j < 8 * g + 8; ++j) raw[j] = sc[lane + 64 * j];
;             } else {
; #pragma unroll
;                 for (int j = 8 * g; j < 8 * g + 8; ++j) raw[j] = 0.f;
;             }
;         }
; #pragma unroll
;         for (int j = 0; j < 64; ++j) key[j] = (j < nreg) ? fkey(raw[j]) : 0u;
; __device__ __forceinline__ void idx_unit(bf16* QB, float* SC, int* SEL, const float* qg, const float* kg, int b, int tp, LAS unsigned char* wl, int lane, bool do_norm) {
;     ...
;         __builtin_amdgcn_fence(__ATOMIC_SEQ_CST, "workgroup");
;         asm volatile("s_waitcnt vmcnt(0)" ::: "memory");
; #pragma unroll 1
;         for (int a = 0; a < 4; ++a) select_query(SC + (row + a) * SEQ, SEL + (row + a) * 256, ce, lane);
	s_cmpk_gt_u32 s6, 0x23f
	s_cselect_b64 s[84:85], -1, 0
	s_cmpk_gt_u32 s6, 0x43f
	s_cselect_b64 s[86:87], -1, 0
	s_cmpk_gt_u32 s6, 0x63f
	s_cselect_b64 s[88:89], -1, 0
	s_cmpk_gt_u32 s6, 0x83f
	s_cselect_b64 s[90:91], -1, 0
	s_cmpk_gt_u32 s6, 0xa3f
	s_cselect_b64 s[92:93], -1, 0
	s_cmpk_gt_u32 s6, 0xc3f
	s_cselect_b64 s[94:95], -1, 0
	s_cmpk_gt_u32 s6, 0xe3f
	s_cselect_b64 s[96:97], -1, 0
	s_cmpk_gt_u32 s6, 0x17f
	s_cselect_b64 s[0:1], -1, 0
	v_writelane_b32 v254, s0, 7
	s_cmpk_gt_u32 s6, 0x1bf
	s_nop 0
	v_writelane_b32 v254, s1, 8
	s_cselect_b64 s[0:1], -1, 0
	v_writelane_b32 v254, s0, 9
	s_cmpk_gt_u32 s6, 0x1ff
	s_waitcnt vmcnt(0)
	s_mov_b32 s3, 0
	v_writelane_b32 v254, s1, 10
	s_cselect_b64 s[0:1], -1, 0
	v_writelane_b32 v254, s0, 11
	s_cmpk_gt_u32 s6, 0x27f
	s_nop 0
	v_writelane_b32 v254, s1, 12
	s_cselect_b64 s[0:1], -1, 0
	v_writelane_b32 v254, s0, 13
	s_cmpk_gt_u32 s6, 0x2bf
	s_nop 0
	v_writelane_b32 v254, s1, 14
	s_cselect_b64 s[0:1], -1, 0
	v_writelane_b32 v254, s0, 15
	s_cmpk_gt_u32 s6, 0x2ff
	s_nop 0
	v_writelane_b32 v254, s1, 16
	s_cselect_b64 s[0:1], -1, 0
	v_writelane_b32 v254, s0, 17
	s_cmpk_gt_u32 s6, 0x33f
	s_nop 0
	v_writelane_b32 v254, s1, 18
	s_cselect_b64 s[0:1], -1, 0
	v_writelane_b32 v254, s0, 19
	s_cmpk_gt_u32 s6, 0x37f
	s_nop 0
	v_writelane_b32 v254, s1, 20
	s_cselect_b64 s[0:1], -1, 0
	v_writelane_b32 v254, s0, 21
	s_cmpk_gt_u32 s6, 0x3bf
	s_nop 0
	v_writelane_b32 v254, s1, 22
	s_cselect_b64 s[0:1], -1, 0
	v_writelane_b32 v254, s0, 23
	s_cmpk_gt_u32 s6, 0x3ff
	s_nop 0
	v_writelane_b32 v254, s1, 24
	s_cselect_b64 s[0:1], -1, 0
	v_writelane_b32 v254, s0, 25
	s_cmpk_gt_u32 s6, 0x47f
	s_nop 0
	v_writelane_b32 v254, s1, 26
	s_cselect_b64 s[0:1], -1, 0
	v_writelane_b32 v254, s0, 27
	s_cmpk_gt_u32 s6, 0x4bf
	s_nop 0
	v_writelane_b32 v254, s1, 28
	s_cselect_b64 s[0:1], -1, 0
	v_writelane_b32 v254, s0, 29
	s_cmpk_gt_u32 s6, 0x4ff
	s_nop 0
	v_writelane_b32 v254, s1, 30
	s_cselect_b64 s[0:1], -1, 0
	v_writelane_b32 v254, s0, 31
	s_cmpk_gt_u32 s6, 0x53f
	s_nop 0
	v_writelane_b32 v254, s1, 32
	s_cselect_b64 s[0:1], -1, 0
	v_writelane_b32 v254, s0, 33
	s_cmpk_gt_u32 s6, 0x57f
	s_nop 0
	v_writelane_b32 v254, s1, 34
	s_cselect_b64 s[0:1], -1, 0
	v_writelane_b32 v254, s0, 35
	s_cmpk_gt_u32 s6, 0x5bf
	s_nop 0
	v_writelane_b32 v254, s1, 36
	s_cselect_b64 s[0:1], -1, 0
	v_writelane_b32 v254, s0, 37
	s_cmpk_gt_u32 s6, 0x5ff
	s_nop 0
	v_writelane_b32 v254, s1, 38
	s_cselect_b64 s[0:1], -1, 0
	v_writelane_b32 v254, s0, 39
	s_cmpk_gt_u32 s6, 0x67f
	s_nop 0
	v_writelane_b32 v254, s1, 40
	s_cselect_b64 s[0:1], -1, 0
	v_writelane_b32 v254, s0, 41
	s_cmpk_gt_u32 s6, 0x6bf
	s_nop 0
	v_writelane_b32 v254, s1, 42
	s_cselect_b64 s[0:1], -1, 0
	v_writelane_b32 v254, s0, 43
	s_cmpk_gt_u32 s6, 0x6ff
	s_nop 0
	v_writelane_b32 v254, s1, 44
	s_cselect_b64 s[0:1], -1, 0
	v_writelane_b32 v254, s0, 45
	s_cmpk_gt_u32 s6, 0x73f
	s_nop 0
	v_writelane_b32 v254, s1, 46
	s_cselect_b64 s[0:1], -1, 0
	v_writelane_b32 v254, s0, 47
	s_cmpk_gt_u32 s6, 0x77f
	s_nop 0
	v_writelane_b32 v254, s1, 48
	s_cselect_b64 s[0:1], -1, 0
	v_writelane_b32 v254, s0, 49
	s_cmpk_gt_u32 s6, 0x7bf
	s_nop 0
	v_writelane_b32 v254, s1, 50
	s_cselect_b64 s[0:1], -1, 0
	v_writelane_b32 v254, s0, 51
	s_cmpk_gt_u32 s6, 0x7ff
	s_nop 0
	v_writelane_b32 v254, s1, 52
	s_cselect_b64 s[0:1], -1, 0
	v_writelane_b32 v254, s0, 53
	s_cmpk_gt_u32 s6, 0x87f
	s_nop 0
	v_writelane_b32 v254, s1, 54
	s_cselect_b64 s[0:1], -1, 0
	v_writelane_b32 v254, s0, 55
	s_cmpk_gt_u32 s6, 0x8bf
	s_nop 0
	v_writelane_b32 v254, s1, 56
	s_cselect_b64 s[0:1], -1, 0
	v_writelane_b32 v254, s0, 57
	s_cmpk_gt_u32 s6, 0x8ff
	s_nop 0
	v_writelane_b32 v254, s1, 58
	s_cselect_b64 s[0:1], -1, 0
	v_writelane_b32 v254, s0, 59
	s_cmpk_gt_u32 s6, 0x93f
	s_nop 0
	v_writelane_b32 v254, s1, 60
	s_cselect_b64 s[0:1], -1, 0
	v_writelane_b32 v254, s0, 61
	s_cmpk_gt_u32 s6, 0x97f
	s_nop 0
	v_writelane_b32 v254, s1, 62
	s_cselect_b64 s[0:1], -1, 0
	v_writelane_b32 v254, s0, 63
	s_cmpk_gt_u32 s6, 0x9bf
	s_nop 0
	v_writelane_b32 v250, s1, 0
	s_cselect_b64 s[0:1], -1, 0
	v_writelane_b32 v250, s0, 1
	s_cmpk_gt_u32 s6, 0x9ff
	s_nop 0
	v_writelane_b32 v250, s1, 2
	s_cselect_b64 s[0:1], -1, 0
	v_writelane_b32 v250, s0, 3
	s_cmpk_gt_u32 s6, 0xa7f
	s_nop 0
	v_writelane_b32 v250, s1, 4
	s_cselect_b64 s[0:1], -1, 0
	v_writelane_b32 v250, s0, 5
	s_cmpk_gt_u32 s6, 0xabf
	s_nop 0
	v_writelane_b32 v250, s1, 6
	s_cselect_b64 s[0:1], -1, 0
	v_writelane_b32 v250, s0, 7
	s_cmpk_gt_u32 s6, 0xaff
	s_nop 0
	v_writelane_b32 v250, s1, 8
	s_cselect_b64 s[0:1], -1, 0
	v_writelane_b32 v250, s0, 9
	s_cmpk_gt_u32 s6, 0xb3f
	s_nop 0
	v_writelane_b32 v250, s1, 10
	s_cselect_b64 s[0:1], -1, 0
	v_writelane_b32 v250, s0, 11
	s_cmpk_gt_u32 s6, 0xb7f
	s_nop 0
	v_writelane_b32 v250, s1, 12
	s_cselect_b64 s[0:1], -1, 0
	v_writelane_b32 v250, s0, 13
	s_cmpk_gt_u32 s6, 0xbbf
	s_nop 0
	v_writelane_b32 v250, s1, 14
	s_cselect_b64 s[0:1], -1, 0
	v_writelane_b32 v250, s0, 15
	s_cmpk_gt_u32 s6, 0xbff
	s_nop 0
	v_writelane_b32 v250, s1, 16
	s_cselect_b64 s[0:1], -1, 0
	v_writelane_b32 v250, s0, 17
	s_cmpk_gt_u32 s6, 0xc7f
	s_nop 0
	v_writelane_b32 v250, s1, 18
	s_cselect_b64 s[0:1], -1, 0
	v_writelane_b32 v250, s0, 19
	s_cmpk_gt_u32 s6, 0xcbf
	s_nop 0
	v_writelane_b32 v250, s1, 20
	s_cselect_b64 s[0:1], -1, 0
	v_writelane_b32 v250, s0, 21
	s_cmpk_gt_u32 s6, 0xcff
	s_nop 0
	v_writelane_b32 v250, s1, 22
	s_cselect_b64 s[0:1], -1, 0
	v_writelane_b32 v250, s0, 23
	s_cmpk_gt_u32 s6, 0xd3f
	s_nop 0
	v_writelane_b32 v250, s1, 24
	s_cselect_b64 s[0:1], -1, 0
	v_writelane_b32 v250, s0, 25
	s_cmpk_gt_u32 s6, 0xd7f
	s_nop 0
	v_writelane_b32 v250, s1, 26
	s_cselect_b64 s[0:1], -1, 0
	v_writelane_b32 v250, s0, 27
	s_cmpk_gt_u32 s6, 0xdbf
	s_nop 0
	v_writelane_b32 v250, s1, 28
	s_cselect_b64 s[0:1], -1, 0
	v_writelane_b32 v250, s0, 29
	s_cmpk_gt_u32 s6, 0xdff
	s_nop 0
	v_writelane_b32 v250, s1, 30
	s_cselect_b64 s[0:1], -1, 0
	s_cmpk_gt_u32 s6, 0xe7f
	s_cselect_b64 s[36:37], -1, 0
	s_cmpk_gt_u32 s6, 0xebf
	s_cselect_b64 s[38:39], -1, 0
	s_cmpk_gt_u32 s6, 0xeff
	s_cselect_b64 s[42:43], -1, 0
	s_cmpk_gt_u32 s6, 0xf3f
	s_cselect_b64 s[44:45], -1, 0
	s_cmpk_gt_u32 s6, 0xf7f
	s_cselect_b64 s[46:47], -1, 0
	s_cmpk_gt_u32 s6, 0xfbf
	s_cselect_b64 s[48:49], -1, 0
	s_cmpk_gt_u32 s6, 0xfff
	v_writelane_b32 v250, s0, 31
	s_cselect_b64 s[50:51], -1, 0
	s_nop 0
	v_writelane_b32 v250, s1, 32
	s_branch .LBB0_247
